# P8: nt stores for the final output (never re-read on the device)
# speedup vs baseline: 1.0071x; 1.0071x over previous
.Lp8r_a_go:
	v_pk_mul_f32 v[2:3], v[32:33], v[32:33]
	v_pk_mul_f32 v[4:5], v[34:35], v[34:35]
	v_pk_fma_f32 v[2:3], v[36:37], v[36:37], v[2:3]
	v_pk_fma_f32 v[4:5], v[38:39], v[38:39], v[4:5]
	v_pk_fma_f32 v[2:3], v[40:41], v[40:41], v[2:3]
	v_pk_fma_f32 v[4:5], v[42:43], v[42:43], v[4:5]
	v_pk_fma_f32 v[2:3], v[44:45], v[44:45], v[2:3]
	v_pk_fma_f32 v[4:5], v[46:47], v[46:47], v[4:5]
	v_pk_fma_f32 v[2:3], v[48:49], v[48:49], v[2:3]
	v_pk_fma_f32 v[4:5], v[50:51], v[50:51], v[4:5]
	v_pk_fma_f32 v[2:3], v[52:53], v[52:53], v[2:3]
	v_pk_fma_f32 v[4:5], v[54:55], v[54:55], v[4:5]
	v_pk_fma_f32 v[2:3], v[56:57], v[56:57], v[2:3]
	v_pk_fma_f32 v[4:5], v[58:59], v[58:59], v[4:5]
	v_pk_fma_f32 v[2:3], v[60:61], v[60:61], v[2:3]
	v_pk_fma_f32 v[4:5], v[62:63], v[62:63], v[4:5]
	v_pk_add_f32 v[2:3], v[2:3], v[4:5]
	s_nop 0
	v_add_f32_e32 v2, v2, v3
	s_nop 1
	v_add_f32_dpp v3, v2, v2 quad_perm:[1,0,3,2] row_mask:0xf bank_mask:0xf
	s_nop 1
	v_add_f32_dpp v2, v3, v3 quad_perm:[2,3,0,1] row_mask:0xf bank_mask:0xf
	s_nop 1
	v_add_f32_dpp v3, v2, v2 row_ror:4 row_mask:0xf bank_mask:0xf
	s_nop 1
	v_add_f32_dpp v2, v3, v3 row_ror:8 row_mask:0xf bank_mask:0xf
	s_nop 1
	v_readlane_b32 s100, v2, 0
	v_readlane_b32 s101, v2, 16
	v_readlane_b32 vcc_lo, v2, 32
	v_readlane_b32 vcc_hi, v2, 48
	v_mov_b32_e32 v3, s100
	v_add_f32_e32 v3, s101, v3
	v_add_f32_e32 v3, vcc_lo, v3
	v_add_f32_e32 v3, vcc_hi, v3
	v_fmamk_f32 v2, v3, 0x3a000000, v28
	v_mul_f32_e32 v3, 0x4b800000, v2
	v_cmp_gt_f32_e32 vcc, 0x800000, v2
	s_nop 1
	v_cndmask_b32_e32 v2, v2, v3, vcc
	v_rsq_f32_e32 v2, v2
	s_nop 0
	v_mul_f32_e32 v3, 0x45800000, v2
	v_cndmask_b32_e32 v2, v2, v3, vcc
	v_pk_mul_f32 v[32:33], v[32:33], v[2:3] op_sel_hi:[1,0]
	v_pk_mul_f32 v[34:35], v[34:35], v[2:3] op_sel_hi:[1,0]
	v_pk_mul_f32 v[32:33], v[32:33], v[96:97]
	v_pk_mul_f32 v[34:35], v[34:35], v[98:99]
	global_store_dwordx4 v0, v[32:35], s[12:13] offset:-4096 nt
	v_pk_mul_f32 v[36:37], v[36:37], v[2:3] op_sel_hi:[1,0]
	v_pk_mul_f32 v[38:39], v[38:39], v[2:3] op_sel_hi:[1,0]
	v_pk_mul_f32 v[36:37], v[36:37], v[100:101]
	v_pk_mul_f32 v[38:39], v[38:39], v[102:103]
	global_store_dwordx4 v0, v[36:39], s[12:13] offset:-3072 nt
	v_pk_mul_f32 v[40:41], v[40:41], v[2:3] op_sel_hi:[1,0]
	v_pk_mul_f32 v[42:43], v[42:43], v[2:3] op_sel_hi:[1,0]
	v_pk_mul_f32 v[40:41], v[40:41], v[104:105]
	v_pk_mul_f32 v[42:43], v[42:43], v[106:107]
	global_store_dwordx4 v0, v[40:43], s[12:13] offset:-2048 nt
	v_pk_mul_f32 v[44:45], v[44:45], v[2:3] op_sel_hi:[1,0]
	v_pk_mul_f32 v[46:47], v[46:47], v[2:3] op_sel_hi:[1,0]
	v_pk_mul_f32 v[44:45], v[44:45], v[108:109]
	v_pk_mul_f32 v[46:47], v[46:47], v[110:111]
	global_store_dwordx4 v0, v[44:47], s[12:13] offset:-1024 nt
	v_pk_mul_f32 v[48:49], v[48:49], v[2:3] op_sel_hi:[1,0]
	v_pk_mul_f32 v[50:51], v[50:51], v[2:3] op_sel_hi:[1,0]
	v_pk_mul_f32 v[48:49], v[48:49], v[112:113]
	v_pk_mul_f32 v[50:51], v[50:51], v[114:115]
	global_store_dwordx4 v0, v[48:51], s[12:13] offset:0 nt
	v_pk_mul_f32 v[52:53], v[52:53], v[2:3] op_sel_hi:[1,0]
	v_pk_mul_f32 v[54:55], v[54:55], v[2:3] op_sel_hi:[1,0]
	v_pk_mul_f32 v[52:53], v[52:53], v[116:117]
	v_pk_mul_f32 v[54:55], v[54:55], v[118:119]
	global_store_dwordx4 v0, v[52:55], s[12:13] offset:1024 nt
	v_pk_mul_f32 v[56:57], v[56:57], v[2:3] op_sel_hi:[1,0]
	v_pk_mul_f32 v[58:59], v[58:59], v[2:3] op_sel_hi:[1,0]
	v_pk_mul_f32 v[56:57], v[56:57], v[120:121]
	v_pk_mul_f32 v[58:59], v[58:59], v[122:123]
	global_store_dwordx4 v0, v[56:59], s[12:13] offset:2048 nt
	v_pk_mul_f32 v[60:61], v[60:61], v[2:3] op_sel_hi:[1,0]
	v_pk_mul_f32 v[62:63], v[62:63], v[2:3] op_sel_hi:[1,0]
	v_pk_mul_f32 v[60:61], v[60:61], v[124:125]
	v_pk_mul_f32 v[62:63], v[62:63], v[126:127]
	global_store_dwordx4 v0, v[60:63], s[12:13] offset:3072 nt
	s_mov_b64 s[12:13], s[8:9]
	s_mov_b32 s3, 1
	s_cmp_eq_u32 s0, 0
	s_cbranch_scc1 .LBB0_841
	s_add_i32 s6, s6, s7
	s_cmp_lt_i32 s6, 0x4000
	s_cselect_b32 s0, 1, 0
	s_cbranch_scc0 .Lp8r_b_nonext
	s_add_u32 s8, s8, s14
	s_addc_u32 s9, s9, 0
	global_load_dwordx4 v[32:35], v0, s[8:9] offset:-4096
	global_load_dwordx4 v[36:39], v0, s[8:9] offset:-3072
	global_load_dwordx4 v[40:43], v0, s[8:9] offset:-2048
	global_load_dwordx4 v[44:47], v0, s[8:9] offset:-1024
	global_load_dwordx4 v[48:51], v0, s[8:9] offset:0
	global_load_dwordx4 v[52:55], v0, s[8:9] offset:1024
	global_load_dwordx4 v[56:59], v0, s[8:9] offset:2048
	global_load_dwordx4 v[60:63], v0, s[8:9] offset:3072
